# p0_mod: 32 loads in flight per iteration; post loop: rcp gates, gain weights hoisted, single counted wait per row
# speedup vs baseline: 1.0464x; 1.0070x over previous
.LBB0_322:
	s_lshl_b32 s14, s0, 3
	s_cmpk_gt_i32 s0, 0x8f
	s_cselect_b64 s[8:9], -1, 0
	s_and_b64 s[2:3], s[8:9], exec
	s_movk_i32 s2, 0xfb80
	s_movk_i32 s1, 0x5800
	s_cselect_b32 s15, s2, 0x5800
	s_cselect_b32 s1, s1, 0x8400
	s_add_i32 s2, s15, s14
	s_waitcnt vmcnt(0)
	v_add_u32_e32 v30, s2, v159
	v_cmp_gt_i32_e32 vcc, s1, v30
	s_waitcnt vmcnt(0) lgkmcnt(0)
	s_barrier
	s_and_saveexec_b64 s[2:3], vcc
	s_cbranch_execz .LBB0_327
	s_lshl_b32 s12, s56, 3
	s_addk_i32 s12, 0xfb80
	v_and_b32_e32 v14, 63, v158
	s_and_b64 s[8:9], s[8:9], exec
	v_mov_b64_e32 v[2:3], s[10:11]
	s_movk_i32 s18, 0x600
	v_mul_u32_u24_e32 v0, 12, v14
	s_cselect_b32 s8, s12, 0x480
	v_mad_i64_i32 v[4:5], s[12:13], v30, s18, v[2:3]
	v_lshlrev_b32_e32 v0, 1, v0
	v_lshl_add_u64 v[8:9], v[4:5], 0, v[0:1]
	v_cmp_lt_u32_e64 s[40:41], 31, v14
	v_mov_b32_e32 v4, 0x800
	v_mad_i64_i32 v[6:7], s[12:13], v30, s74, v[2:3]
	v_cndmask_b32_e64 v4, v4, v210, s[40:41]
	v_mov_b32_e32 v5, v1
	s_mov_b32 s9, 0xc600000
	v_lshl_add_u64 v[14:15], v[6:7], 0, v[4:5]
	v_and_b32_e32 v6, 31, v158
	v_add_co_u32_e32 v16, vcc, s9, v8
	v_mul_u32_u24_e32 v18, 12, v6
	s_nop 0
	v_addc_co_u32_e32 v17, vcc, 0, v9, vcc
	s_mov_b32 s9, 0xf780000
	v_lshl_add_u64 v[10:11], v[8:9], 0, s[28:29]
	v_lshl_add_u64 v[12:13], v[8:9], 0, s[30:31]
	v_lshlrev_b32_e32 v6, 1, v18
	v_mov_b32_e32 v7, v1
	v_add_co_u32_e32 v8, vcc, s9, v8
	v_lshl_add_u64 v[14:15], v[14:15], 0, v[6:7]
	s_nop 0
	v_addc_co_u32_e32 v9, vcc, 0, v9, vcc
	global_load_dwordx4 v[22:25], v[16:17], off
	global_load_dwordx2 v[48:49], v[10:11], off offset:16
	global_load_dwordx4 v[26:29], v[8:9], off
	global_load_dwordx2 v[50:51], v[12:13], off offset:16
	global_load_dwordx2 v[44:45], v[14:15], off offset:16
	s_nop 0
	global_load_dwordx4 v[14:17], v[14:15], off
	v_and_b32_e32 v9, 64, v209
	v_xor_b32_e32 v8, 1, v209
	v_add_u32_e32 v9, 64, v9
	v_cmp_lt_i32_e32 vcc, v8, v9
	s_mul_i32 s12, s44, 0x180
	s_ashr_i32 s13, s12, 31
	v_cndmask_b32_e32 v8, v209, v8, vcc
	v_lshlrev_b32_e32 v72, 2, v8
	v_xor_b32_e32 v8, 2, v209
	v_cmp_lt_i32_e32 vcc, v8, v9
	v_ashrrev_i32_e32 v31, 31, v30
	v_lshlrev_b32_e32 v10, 2, v18
	v_cndmask_b32_e32 v8, v209, v8, vcc
	v_lshlrev_b32_e32 v73, 2, v8
	v_xor_b32_e32 v8, 4, v209
	v_cmp_lt_i32_e32 vcc, v8, v9
	v_mov_b32_e32 v9, v1
	v_mov_b32_e32 v11, v1
	v_cndmask_b32_e32 v8, v209, v8, vcc
	v_lshlrev_b32_e32 v74, 2, v8
	v_cndmask_b32_e64 v8, v211, v212, s[40:41]
	v_lshl_add_u64 v[8:9], s[54:55], 0, v[8:9]
	global_load_dwordx2 v[8:9], v[8:9], off
	s_ashr_i32 s9, s8, 31
	s_movk_i32 s16, 0x600
	s_waitcnt vmcnt(0)
	v_lshl_add_u64 v[8:9], s[12:13], 2, v[8:9]
	s_load_dwordx2 s[12:13], s[54:55], 0x158
	v_lshl_add_u64 v[32:33], v[8:9], 0, v[10:11]
	global_load_dwordx4 v[80:83], v[32:33], off
	global_load_dwordx4 v[84:87], v[32:33], off offset:16
	global_load_dwordx4 v[88:91], v[32:33], off offset:32
	s_waitcnt vmcnt(0)
	v_lshlrev_b64 v[8:9], 11, v[30:31]
	s_waitcnt lgkmcnt(0)
	v_lshl_add_u64 v[34:35], s[12:13], 0, v[8:9]
	s_lshl_b64 s[12:13], s[8:9], 11
	s_add_i32 s9, s8, s15
	s_add_i32 s14, s14, s9
	v_add_u32_e32 v8, s14, v159
	v_mad_i64_i32 v[4:5], s[14:15], v8, s74, v[4:5]
	v_lshl_add_u64 v[4:5], v[4:5], 0, v[6:7]
	v_lshl_add_u64 v[4:5], s[10:11], 0, v[4:5]
	v_mad_i64_i32 v[38:39], s[14:15], v8, s18, v[2:3]
	v_lshl_add_u64 v[36:37], v[4:5], 0, 8
	s_mul_hi_i32 s11, s8, 0x1800
	s_mul_i32 s10, s8, 0x1800
	s_mul_hi_i32 s15, s8, 0x600
	s_mul_i32 s14, s8, 0x600
	s_mov_b64 s[18:19], 0
	s_branch .LBB0_325
.LBB0_324:
	s_or_b64 exec, exec, s[22:23]
	v_and_b32_e32 v18, 0xffff0000, v24
	v_lshlrev_b32_e32 v19, 16, v24
	v_and_b32_e32 v20, 0xffff0000, v28
	v_lshlrev_b32_e32 v21, 16, v28
	v_pk_add_f32 v[52:53], v[18:19], v[20:21]
	v_and_b32_e32 v18, 0xffff0000, v25
	v_lshlrev_b32_e32 v19, 16, v25
	v_and_b32_e32 v20, 0xffff0000, v29
	v_lshlrev_b32_e32 v21, 16, v29
	v_pk_add_f32 v[54:55], v[18:19], v[20:21]
	v_and_b32_e32 v18, 0xffff0000, v49
	v_lshlrev_b32_e32 v19, 16, v49
	v_and_b32_e32 v20, 0xffff0000, v51
	v_lshlrev_b32_e32 v21, 16, v51
	v_pk_add_f32 v[60:61], v[18:19], v[20:21]
	v_lshlrev_b32_e32 v18, 16, v23
	v_and_b32_e32 v19, 0xffff0000, v23
	v_lshlrev_b32_e32 v20, 16, v27
	v_and_b32_e32 v21, 0xffff0000, v27
	v_pk_add_f32 v[56:57], v[18:19], v[20:21]
	v_lshlrev_b32_e32 v19, 16, v15
	v_and_b32_e32 v15, 0xffff0000, v15
	v_mul_f32_e32 v18, 0xbfb8aa3b, v19
	v_cndmask_b32_e64 v21, v15, 1.0, s[40:41]
	v_mul_f32_e32 v15, 0xbfb8aa3b, v15
	v_exp_f32_e32 v18, v18
	v_cndmask_b32_e64 v20, v19, 1.0, s[40:41]
	v_exp_f32_e32 v19, v15
	v_lshlrev_b32_e32 v58, 16, v22
	v_and_b32_e32 v59, 0xffff0000, v22
	v_lshlrev_b32_e32 v22, 16, v26
	v_pk_add_f32 v[18:19], v[18:19], 1.0 op_sel_hi:[1,0]
	v_lshl_add_u64 v[24:25], v[34:35], 0, v[0:1]
	v_rcp_f32_e32 v15, v19
	v_lshl_add_u64 v[34:35], v[34:35], 0, s[12:13]
	v_lshl_add_u64 v[36:37], v[36:37], 0, s[10:11]
	v_lshl_add_u64 v[38:39], v[38:39], 0, s[14:15]
	v_mul_f32_e32 v29, v21, v15
	v_rcp_f32_e32 v15, v18
	v_and_b32_e32 v23, 0xffff0000, v26
	v_pk_add_f32 v[22:23], v[58:59], v[22:23]
	v_mul_f32_e32 v28, v20, v15
	v_add_f32_e32 v15, 0, v22
	v_add_f32_e32 v26, v23, v15
	v_lshlrev_b32_e32 v15, 16, v14
	v_and_b32_e32 v27, 0xffff0000, v14
	v_mul_f32_e32 v14, 0xbfb8aa3b, v15
	v_cndmask_b32_e64 v31, v15, 1.0, s[40:41]
	v_mul_f32_e32 v15, 0xbfb8aa3b, v27
	v_exp_f32_e32 v14, v14
	v_exp_f32_e32 v15, v15
	v_cndmask_b32_e64 v49, v27, 1.0, s[40:41]
	v_add_f32_e32 v26, v56, v26
	v_add_f32_e32 v26, v57, v26
	v_pk_add_f32 v[14:15], v[14:15], 1.0 op_sel_hi:[1,0]
	v_add_f32_e32 v26, v53, v26
	v_rcp_f32_e32 v27, v15
	v_add_f32_e32 v26, v52, v26
	v_add_f32_e32 v26, v55, v26
	v_mul_f32_e32 v15, v49, v27
	v_rcp_f32_e32 v27, v14
	s_nop 0
	v_mul_f32_e32 v14, v31, v27
	v_add_f32_e32 v31, v54, v26
	v_and_b32_e32 v26, 0xffff0000, v48
	v_lshlrev_b32_e32 v27, 16, v48
	v_and_b32_e32 v48, 0xffff0000, v50
	v_lshlrev_b32_e32 v49, 16, v50
	v_pk_add_f32 v[26:27], v[26:27], v[48:49]
	s_nop 0
	v_add_f32_e32 v31, v27, v31
	v_add_f32_e32 v31, v26, v31
	v_add_f32_e32 v31, v61, v31
	v_add_f32_e32 v31, v60, v31
	ds_bpermute_b32 v48, v72, v31
	s_waitcnt lgkmcnt(0)
	v_add_f32_e32 v31, v31, v48
	ds_bpermute_b32 v48, v73, v31
	s_waitcnt lgkmcnt(0)
	v_add_f32_e32 v31, v31, v48
	ds_bpermute_b32 v48, v74, v31
	s_waitcnt lgkmcnt(0)
	v_add_f32_e32 v31, v31, v48
	v_mul_f32_e32 v70, 0x3c2aaaab, v31
	v_lshlrev_b32_e32 v31, 16, v17
	v_and_b32_e32 v17, 0xffff0000, v17
	v_pk_add_f32 v[48:49], v[54:55], v[70:71] op_sel_hi:[1,0] neg_lo:[0,1] neg_hi:[0,1]
	v_mul_f32_e32 v50, 0xbfb8aa3b, v31
	v_cndmask_b32_e64 v54, v17, 1.0, s[40:41]
	v_mul_f32_e32 v17, 0xbfb8aa3b, v17
	v_exp_f32_e32 v50, v50
	v_exp_f32_e32 v51, v17
	v_pk_add_f32 v[58:59], v[22:23], v[70:71] op_sel_hi:[1,0] neg_lo:[0,1] neg_hi:[0,1]
	v_pk_add_f32 v[56:57], v[56:57], v[70:71] op_sel_hi:[1,0] neg_lo:[0,1] neg_hi:[0,1]
	v_pk_add_f32 v[26:27], v[26:27], v[70:71] op_sel_hi:[1,0] neg_lo:[0,1] neg_hi:[0,1]
	v_pk_add_f32 v[50:51], v[50:51], 1.0 op_sel_hi:[1,0]
	v_pk_add_f32 v[22:23], v[60:61], v[70:71] op_sel_hi:[1,0] neg_lo:[0,1] neg_hi:[0,1]
	v_rcp_f32_e32 v17, v51
	v_cndmask_b32_e64 v31, v31, 1.0, s[40:41]
	v_pk_mul_f32 v[64:65], v[58:59], v[58:59]
	v_pk_mul_f32 v[66:67], v[56:57], v[56:57]
	v_mul_f32_e32 v51, v54, v17
	v_rcp_f32_e32 v17, v50
	v_pk_mul_f32 v[68:69], v[48:49], v[48:49]
	v_pk_mul_f32 v[62:63], v[26:27], v[26:27]
	v_pk_mul_f32 v[60:61], v[22:23], v[22:23]
	v_mul_f32_e32 v50, v31, v17
	v_lshlrev_b32_e32 v17, 16, v16
	v_and_b32_e32 v31, 0xffff0000, v16
	v_mul_f32_e32 v16, 0xbfb8aa3b, v17
	v_cndmask_b32_e64 v54, v17, 1.0, s[40:41]
	v_mul_f32_e32 v17, 0xbfb8aa3b, v31
	v_exp_f32_e32 v16, v16
	v_exp_f32_e32 v17, v17
	v_cndmask_b32_e64 v55, v31, 1.0, s[40:41]
	v_pk_add_f32 v[70:71], v[52:53], v[70:71] op_sel_hi:[1,0] neg_lo:[0,1] neg_hi:[0,1]
	v_pk_add_f32 v[16:17], v[16:17], 1.0 op_sel_hi:[1,0]
	s_nop 0
	v_rcp_f32_e32 v31, v17
	v_pk_mul_f32 v[52:53], v[70:71], v[70:71]
	v_mul_f32_e32 v55, v55, v31
	v_rcp_f32_e32 v17, v16
	s_nop 0
	v_mul_f32_e32 v54, v54, v17
	v_add_f32_e32 v16, v64, v65
	v_add_f32_e32 v16, v66, v16
	v_add_f32_e32 v16, v67, v16
	v_add_f32_e32 v16, v53, v16
	v_add_f32_e32 v16, v52, v16
	v_add_f32_e32 v16, v69, v16
	v_add_f32_e32 v16, v68, v16
	v_add_f32_e32 v16, v63, v16
	v_add_f32_e32 v16, v62, v16
	v_add_f32_e32 v16, v61, v16
	v_add_f32_e32 v16, v60, v16
	ds_bpermute_b32 v17, v72, v16
	s_waitcnt lgkmcnt(0)
	v_add_f32_e32 v16, v16, v17
	ds_bpermute_b32 v17, v73, v16
	s_waitcnt lgkmcnt(0)
	v_add_f32_e32 v16, v16, v17
	ds_bpermute_b32 v17, v74, v16
	s_waitcnt lgkmcnt(0)
	v_add_f32_e32 v16, v16, v17
	v_fmamk_f32 v16, v16, 0x3c2aaaab, v208
	v_cmp_gt_f32_e32 vcc, s5, v16
	v_mul_f32_e32 v17, 0x4b800000, v16
	s_nop 0
	v_cndmask_b32_e32 v16, v16, v17, vcc
	v_rsq_f32_e32 v16, v16
	s_nop 0
	v_mul_f32_e32 v17, 0x45800000, v16
	v_cndmask_b32_e32 v52, v16, v17, vcc
	v_pk_mul_f32 v[16:17], v[58:59], v[52:53] op_sel_hi:[1,0]
	v_mul_f32_e32 v23, v23, v52
	v_pk_mul_f32 v[16:17], v[80:81], v[16:17]
	v_pk_mul_f32 v[18:19], v[70:71], v[52:53] op_sel_hi:[1,0]
	v_pk_mul_f32 v[14:15], v[14:15], v[16:17]
	v_pk_mul_f32 v[16:17], v[56:57], v[52:53] op_sel_hi:[1,0]
	v_cvt_pk_bf16_f32 v14, v14, v15
	v_pk_mul_f32 v[16:17], v[82:83], v[16:17]
	v_and_b32_e32 v20, 0xffff0000, v45
	v_pk_mul_f32 v[16:17], v[28:29], v[16:17]
	s_nop 0
	v_cvt_pk_bf16_f32 v15, v16, v17
	global_store_dwordx2 v[24:25], v[14:15], off offset:512
	v_pk_mul_f32 v[14:15], v[84:85], v[18:19] op_sel:[0,1] op_sel_hi:[1,0]
	v_pk_mul_f32 v[18:19], v[48:49], v[52:53] op_sel_hi:[1,0]
	v_pk_mul_f32 v[14:15], v[54:55], v[14:15]
	v_pk_mul_f32 v[16:17], v[86:87], v[18:19] op_sel:[0,1] op_sel_hi:[1,0]
	v_cvt_pk_bf16_f32 v14, v14, v15
	v_pk_mul_f32 v[16:17], v[50:51], v[16:17]
	v_and_b32_e32 v18, 0xffff0000, v44
	v_cvt_pk_bf16_f32 v15, v16, v17
	global_store_dwordx2 v[24:25], v[14:15], off offset:520
	v_lshlrev_b32_e32 v14, 16, v44
	v_cndmask_b32_e64 v15, v14, 1.0, s[40:41]
	v_mul_f32_e32 v14, 0xbfb8aa3b, v14
	v_exp_f32_e32 v14, v14
	v_lshlrev_b32_e32 v19, 16, v45
	v_add_f32_e32 v14, 1.0, v14
	v_rcp_f32_e32 v16, v14
	s_nop 0
	v_mul_f32_e32 v21, v15, v16
	v_cndmask_b32_e64 v28, v18, 1.0, s[40:41]
	v_mul_f32_e32 v18, 0xbfb8aa3b, v18
	v_exp_f32_e32 v18, v18
	v_mul_f32_e32 v16, v90, v23
	v_add_f32_e32 v18, 1.0, v18
	v_rcp_f32_e32 v29, v18
	s_nop 0
	v_mul_f32_e32 v18, v28, v29
	v_cndmask_b32_e64 v28, v19, 1.0, s[40:41]
	v_mul_f32_e32 v19, 0xbfb8aa3b, v19
	v_exp_f32_e32 v19, v19
	s_nop 0
	v_add_f32_e32 v19, 1.0, v19
	v_rcp_f32_e32 v29, v19
	s_nop 0
	v_mul_f32_e32 v19, v28, v29
	v_cndmask_b32_e64 v28, v20, 1.0, s[40:41]
	v_mul_f32_e32 v20, 0xbfb8aa3b, v20
	v_exp_f32_e32 v20, v20
	v_mul_f32_e32 v16, v19, v16
	v_mul_f32_e32 v19, v26, v52
	v_mul_f32_e32 v15, v89, v19
	v_add_f32_e32 v20, 1.0, v20
	v_rcp_f32_e32 v29, v20
	v_mul_f32_e32 v15, v18, v15
	v_mul_f32_e32 v18, v27, v52
	v_mul_f32_e32 v14, v88, v18
	v_mul_f32_e32 v18, v22, v52
	v_mul_f32_e32 v20, v28, v29
	v_mul_f32_e32 v17, v91, v18
	v_mul_f32_e32 v14, v21, v14
	v_mul_f32_e32 v17, v20, v17
	v_cvt_pk_bf16_f32 v14, v14, v15
	v_cvt_pk_bf16_f32 v15, v16, v17
	global_store_dwordx2 v[24:25], v[14:15], off offset:528
	s_waitcnt vmcnt(3)
	v_mov_b64_e32 v[50:51], v[42:43]
	v_mov_b64_e32 v[22:23], v[2:3]
	v_mov_b64_e32 v[24:25], v[4:5]
	v_mov_b64_e32 v[48:49], v[40:41]
	v_mov_b64_e32 v[26:27], v[6:7]
	v_mov_b64_e32 v[28:29], v[8:9]
	v_mov_b64_e32 v[14:15], v[10:11]
	v_mov_b64_e32 v[16:17], v[12:13]
	v_mov_b64_e32 v[44:45], v[46:47]
	s_andn2_b64 exec, exec, s[18:19]
	s_cbranch_execz .LBB0_327

.LBB0_778:
	s_or_b64 exec, exec, s[14:15]
	s_mul_hi_i32 s14, s1, 0x2aaaaaab
	s_lshr_b32 s15, s14, 31
	s_ashr_i32 s14, s14, 3
	s_add_i32 s18, s14, s15
	s_mul_i32 s14, s18, 48
	s_sub_i32 s14, s1, s14
	v_lshl_or_b32 v12, s14, 7, v23
	v_ashrrev_i32_e32 v13, 31, v12
	v_lshlrev_b64 v[14:15], 2, v[12:13]
	v_mad_i64_i32 v[14:15], s[14:15], s18, v227, v[14:15]
	v_mov_b32_e32 v0, 0
	v_lshl_add_u64 v[14:15], v[8:9], 0, v[14:15]
	s_mov_b64 s[14:15], 0
	v_mov_b32_e32 v11, v24
	v_mov_b32_e32 v16, 0
	v_mov_b32_e32 v17, v0
	v_mov_b32_e32 v18, 0
	v_mov_b32_e32 v19, v0
	s_waitcnt lgkmcnt(0)
	s_barrier
	v_and_b32_e32 v70, 0x7f, v12
	v_lshlrev_b32_e32 v70, 2, v70
	v_sub_co_u32_e32 v72, vcc, v14, v70
	s_nop 1
	v_subbrev_co_u32_e32 v73, vcc, 0, v15, vcc
	s_nop 0
	v_readfirstlane_b32 s22, v72
	v_readfirstlane_b32 s23, v73
	s_mov_b32 s19, 8
	s_nop 3
.LBB0_779:
	global_load_dword v74, v70, s[22:23]
	s_add_u32 s22, s22, 0x6000
	s_addc_u32 s23, s23, 0
	global_load_dword v75, v70, s[22:23]
	s_add_u32 s22, s22, 0x6000
	s_addc_u32 s23, s23, 0
	global_load_dword v76, v70, s[22:23]
	s_add_u32 s22, s22, 0x6000
	s_addc_u32 s23, s23, 0
	global_load_dword v77, v70, s[22:23]
	s_add_u32 s22, s22, 0x6000
	s_addc_u32 s23, s23, 0
	global_load_dword v78, v70, s[22:23]
	s_add_u32 s22, s22, 0x6000
	s_addc_u32 s23, s23, 0
	global_load_dword v79, v70, s[22:23]
	s_add_u32 s22, s22, 0x6000
	s_addc_u32 s23, s23, 0
	global_load_dword v80, v70, s[22:23]
	s_add_u32 s22, s22, 0x6000
	s_addc_u32 s23, s23, 0
	global_load_dword v81, v70, s[22:23]
	s_add_u32 s22, s22, 0x6000
	s_addc_u32 s23, s23, 0
	global_load_dword v82, v70, s[22:23]
	s_add_u32 s22, s22, 0x6000
	s_addc_u32 s23, s23, 0
	global_load_dword v83, v70, s[22:23]
	s_add_u32 s22, s22, 0x6000
	s_addc_u32 s23, s23, 0
	global_load_dword v84, v70, s[22:23]
	s_add_u32 s22, s22, 0x6000
	s_addc_u32 s23, s23, 0
	global_load_dword v85, v70, s[22:23]
	s_add_u32 s22, s22, 0x6000
	s_addc_u32 s23, s23, 0
	global_load_dword v86, v70, s[22:23]
	s_add_u32 s22, s22, 0x6000
	s_addc_u32 s23, s23, 0
	global_load_dword v87, v70, s[22:23]
	s_add_u32 s22, s22, 0x6000
	s_addc_u32 s23, s23, 0
	global_load_dword v88, v70, s[22:23]
	s_add_u32 s22, s22, 0x6000
	s_addc_u32 s23, s23, 0
	global_load_dword v89, v70, s[22:23]
	s_add_u32 s22, s22, 0x6000
	s_addc_u32 s23, s23, 0
	global_load_dword v90, v70, s[22:23]
	s_add_u32 s22, s22, 0x6000
	s_addc_u32 s23, s23, 0
	global_load_dword v91, v70, s[22:23]
	s_add_u32 s22, s22, 0x6000
	s_addc_u32 s23, s23, 0
	global_load_dword v92, v70, s[22:23]
	s_add_u32 s22, s22, 0x6000
	s_addc_u32 s23, s23, 0
	global_load_dword v93, v70, s[22:23]
	s_add_u32 s22, s22, 0x6000
	s_addc_u32 s23, s23, 0
	global_load_dword v94, v70, s[22:23]
	s_add_u32 s22, s22, 0x6000
	s_addc_u32 s23, s23, 0
	global_load_dword v95, v70, s[22:23]
	s_add_u32 s22, s22, 0x6000
	s_addc_u32 s23, s23, 0
	global_load_dword v96, v70, s[22:23]
	s_add_u32 s22, s22, 0x6000
	s_addc_u32 s23, s23, 0
	global_load_dword v97, v70, s[22:23]
	s_add_u32 s22, s22, 0x6000
	s_addc_u32 s23, s23, 0
	global_load_dword v98, v70, s[22:23]
	s_add_u32 s22, s22, 0x6000
	s_addc_u32 s23, s23, 0
	global_load_dword v99, v70, s[22:23]
	s_add_u32 s22, s22, 0x6000
	s_addc_u32 s23, s23, 0
	global_load_dword v100, v70, s[22:23]
	s_add_u32 s22, s22, 0x6000
	s_addc_u32 s23, s23, 0
	global_load_dword v101, v70, s[22:23]
	s_add_u32 s22, s22, 0x6000
	s_addc_u32 s23, s23, 0
	global_load_dword v102, v70, s[22:23]
	s_add_u32 s22, s22, 0x6000
	s_addc_u32 s23, s23, 0
	global_load_dword v103, v70, s[22:23]
	s_add_u32 s22, s22, 0x6000
	s_addc_u32 s23, s23, 0
	global_load_dword v104, v70, s[22:23]
	s_add_u32 s22, s22, 0x6000
	s_addc_u32 s23, s23, 0
	global_load_dword v105, v70, s[22:23]
	s_add_u32 s22, s22, 0x6000
	s_addc_u32 s23, s23, 0
	ds_read_b128 v[106:109], v11
	ds_read_b128 v[110:113], v11 offset:4096
	ds_read_b128 v[114:117], v11 offset:8192
	ds_read_b128 v[118:121], v11 offset:12288
	ds_read_b128 v[122:125], v11 offset:16384
	ds_read_b128 v[126:129], v11 offset:16
	ds_read_b128 v[130:133], v11 offset:4112
	ds_read_b128 v[134:137], v11 offset:8208
	ds_read_b128 v[138:141], v11 offset:12304
	ds_read_b128 v[142:145], v11 offset:16400
	s_waitcnt vmcnt(28) lgkmcnt(5)
	v_fmac_f32_e32 v16, v74, v106
	v_fmac_f32_e32 v17, v74, v110
	v_fmac_f32_e32 v18, v74, v114
	v_fmac_f32_e32 v19, v74, v118
	v_fmac_f32_e32 v0, v74, v122
	v_fmac_f32_e32 v16, v75, v107
	v_fmac_f32_e32 v17, v75, v111
	v_fmac_f32_e32 v18, v75, v115
	v_fmac_f32_e32 v19, v75, v119
	v_fmac_f32_e32 v0, v75, v123
	v_fmac_f32_e32 v16, v76, v108
	v_fmac_f32_e32 v17, v76, v112
	v_fmac_f32_e32 v18, v76, v116
	v_fmac_f32_e32 v19, v76, v120
	v_fmac_f32_e32 v0, v76, v124
	v_fmac_f32_e32 v16, v77, v109
	v_fmac_f32_e32 v17, v77, v113
	v_fmac_f32_e32 v18, v77, v117
	v_fmac_f32_e32 v19, v77, v121
	v_fmac_f32_e32 v0, v77, v125
	ds_read_b128 v[106:109], v11 offset:32
	ds_read_b128 v[110:113], v11 offset:4128
	ds_read_b128 v[114:117], v11 offset:8224
	ds_read_b128 v[118:121], v11 offset:12320
	ds_read_b128 v[122:125], v11 offset:16416
	s_waitcnt vmcnt(24) lgkmcnt(5)
	v_fmac_f32_e32 v16, v78, v126
	v_fmac_f32_e32 v17, v78, v130
	v_fmac_f32_e32 v18, v78, v134
	v_fmac_f32_e32 v19, v78, v138
	v_fmac_f32_e32 v0, v78, v142
	v_fmac_f32_e32 v16, v79, v127
	v_fmac_f32_e32 v17, v79, v131
	v_fmac_f32_e32 v18, v79, v135
	v_fmac_f32_e32 v19, v79, v139
	v_fmac_f32_e32 v0, v79, v143
	v_fmac_f32_e32 v16, v80, v128
	v_fmac_f32_e32 v17, v80, v132
	v_fmac_f32_e32 v18, v80, v136
	v_fmac_f32_e32 v19, v80, v140
	v_fmac_f32_e32 v0, v80, v144
	v_fmac_f32_e32 v16, v81, v129
	v_fmac_f32_e32 v17, v81, v133
	v_fmac_f32_e32 v18, v81, v137
	v_fmac_f32_e32 v19, v81, v141
	v_fmac_f32_e32 v0, v81, v145
	ds_read_b128 v[126:129], v11 offset:48
	ds_read_b128 v[130:133], v11 offset:4144
	ds_read_b128 v[134:137], v11 offset:8240
	ds_read_b128 v[138:141], v11 offset:12336
	ds_read_b128 v[142:145], v11 offset:16432
	s_waitcnt vmcnt(20) lgkmcnt(5)
	v_fmac_f32_e32 v16, v82, v106
	v_fmac_f32_e32 v17, v82, v110
	v_fmac_f32_e32 v18, v82, v114
	v_fmac_f32_e32 v19, v82, v118
	v_fmac_f32_e32 v0, v82, v122
	v_fmac_f32_e32 v16, v83, v107
	v_fmac_f32_e32 v17, v83, v111
	v_fmac_f32_e32 v18, v83, v115
	v_fmac_f32_e32 v19, v83, v119
	v_fmac_f32_e32 v0, v83, v123
	v_fmac_f32_e32 v16, v84, v108
	v_fmac_f32_e32 v17, v84, v112
	v_fmac_f32_e32 v18, v84, v116
	v_fmac_f32_e32 v19, v84, v120
	v_fmac_f32_e32 v0, v84, v124
	v_fmac_f32_e32 v16, v85, v109
	v_fmac_f32_e32 v17, v85, v113
	v_fmac_f32_e32 v18, v85, v117
	v_fmac_f32_e32 v19, v85, v121
	v_fmac_f32_e32 v0, v85, v125
	ds_read_b128 v[106:109], v11 offset:64
	ds_read_b128 v[110:113], v11 offset:4160
	ds_read_b128 v[114:117], v11 offset:8256
	ds_read_b128 v[118:121], v11 offset:12352
	ds_read_b128 v[122:125], v11 offset:16448
	s_waitcnt vmcnt(16) lgkmcnt(5)
	v_fmac_f32_e32 v16, v86, v126
	v_fmac_f32_e32 v17, v86, v130
	v_fmac_f32_e32 v18, v86, v134
	v_fmac_f32_e32 v19, v86, v138
	v_fmac_f32_e32 v0, v86, v142
	v_fmac_f32_e32 v16, v87, v127
	v_fmac_f32_e32 v17, v87, v131
	v_fmac_f32_e32 v18, v87, v135
	v_fmac_f32_e32 v19, v87, v139
	v_fmac_f32_e32 v0, v87, v143
	v_fmac_f32_e32 v16, v88, v128
	v_fmac_f32_e32 v17, v88, v132
	v_fmac_f32_e32 v18, v88, v136
	v_fmac_f32_e32 v19, v88, v140
	v_fmac_f32_e32 v0, v88, v144
	v_fmac_f32_e32 v16, v89, v129
	v_fmac_f32_e32 v17, v89, v133
	v_fmac_f32_e32 v18, v89, v137
	v_fmac_f32_e32 v19, v89, v141
	v_fmac_f32_e32 v0, v89, v145
	ds_read_b128 v[126:129], v11 offset:80
	ds_read_b128 v[130:133], v11 offset:4176
	ds_read_b128 v[134:137], v11 offset:8272
	ds_read_b128 v[138:141], v11 offset:12368
	ds_read_b128 v[142:145], v11 offset:16464
	s_waitcnt vmcnt(12) lgkmcnt(5)
	v_fmac_f32_e32 v16, v90, v106
	v_fmac_f32_e32 v17, v90, v110
	v_fmac_f32_e32 v18, v90, v114
	v_fmac_f32_e32 v19, v90, v118
	v_fmac_f32_e32 v0, v90, v122
	v_fmac_f32_e32 v16, v91, v107
	v_fmac_f32_e32 v17, v91, v111
	v_fmac_f32_e32 v18, v91, v115
	v_fmac_f32_e32 v19, v91, v119
	v_fmac_f32_e32 v0, v91, v123
	v_fmac_f32_e32 v16, v92, v108
	v_fmac_f32_e32 v17, v92, v112
	v_fmac_f32_e32 v18, v92, v116
	v_fmac_f32_e32 v19, v92, v120
	v_fmac_f32_e32 v0, v92, v124
	v_fmac_f32_e32 v16, v93, v109
	v_fmac_f32_e32 v17, v93, v113
	v_fmac_f32_e32 v18, v93, v117
	v_fmac_f32_e32 v19, v93, v121
	v_fmac_f32_e32 v0, v93, v125
	ds_read_b128 v[106:109], v11 offset:96
	ds_read_b128 v[110:113], v11 offset:4192
	ds_read_b128 v[114:117], v11 offset:8288
	ds_read_b128 v[118:121], v11 offset:12384
	ds_read_b128 v[122:125], v11 offset:16480
	s_waitcnt vmcnt(8) lgkmcnt(5)
	v_fmac_f32_e32 v16, v94, v126
	v_fmac_f32_e32 v17, v94, v130
	v_fmac_f32_e32 v18, v94, v134
	v_fmac_f32_e32 v19, v94, v138
	v_fmac_f32_e32 v0, v94, v142
	v_fmac_f32_e32 v16, v95, v127
	v_fmac_f32_e32 v17, v95, v131
	v_fmac_f32_e32 v18, v95, v135
	v_fmac_f32_e32 v19, v95, v139
	v_fmac_f32_e32 v0, v95, v143
	v_fmac_f32_e32 v16, v96, v128
	v_fmac_f32_e32 v17, v96, v132
	v_fmac_f32_e32 v18, v96, v136
	v_fmac_f32_e32 v19, v96, v140
	v_fmac_f32_e32 v0, v96, v144
	v_fmac_f32_e32 v16, v97, v129
	v_fmac_f32_e32 v17, v97, v133
	v_fmac_f32_e32 v18, v97, v137
	v_fmac_f32_e32 v19, v97, v141
	v_fmac_f32_e32 v0, v97, v145
	ds_read_b128 v[126:129], v11 offset:112
	ds_read_b128 v[130:133], v11 offset:4208
	ds_read_b128 v[134:137], v11 offset:8304
	ds_read_b128 v[138:141], v11 offset:12400
	ds_read_b128 v[142:145], v11 offset:16496
	s_waitcnt vmcnt(4) lgkmcnt(5)
	v_fmac_f32_e32 v16, v98, v106
	v_fmac_f32_e32 v17, v98, v110
	v_fmac_f32_e32 v18, v98, v114
	v_fmac_f32_e32 v19, v98, v118
	v_fmac_f32_e32 v0, v98, v122
	v_fmac_f32_e32 v16, v99, v107
	v_fmac_f32_e32 v17, v99, v111
	v_fmac_f32_e32 v18, v99, v115
	v_fmac_f32_e32 v19, v99, v119
	v_fmac_f32_e32 v0, v99, v123
	v_fmac_f32_e32 v16, v100, v108
	v_fmac_f32_e32 v17, v100, v112
	v_fmac_f32_e32 v18, v100, v116
	v_fmac_f32_e32 v19, v100, v120
	v_fmac_f32_e32 v0, v100, v124
	v_fmac_f32_e32 v16, v101, v109
	v_fmac_f32_e32 v17, v101, v113
	v_fmac_f32_e32 v18, v101, v117
	v_fmac_f32_e32 v19, v101, v121
	v_fmac_f32_e32 v0, v101, v125
	s_waitcnt vmcnt(0) lgkmcnt(0)
	v_fmac_f32_e32 v16, v102, v126
	v_fmac_f32_e32 v17, v102, v130
	v_fmac_f32_e32 v18, v102, v134
	v_fmac_f32_e32 v19, v102, v138
	v_fmac_f32_e32 v0, v102, v142
	v_fmac_f32_e32 v16, v103, v127
	v_fmac_f32_e32 v17, v103, v131
	v_fmac_f32_e32 v18, v103, v135
	v_fmac_f32_e32 v19, v103, v139
	v_fmac_f32_e32 v0, v103, v143
	v_fmac_f32_e32 v16, v104, v128
	v_fmac_f32_e32 v17, v104, v132
	v_fmac_f32_e32 v18, v104, v136
	v_fmac_f32_e32 v19, v104, v140
	v_fmac_f32_e32 v0, v104, v144
	v_fmac_f32_e32 v16, v105, v129
	v_fmac_f32_e32 v17, v105, v133
	v_fmac_f32_e32 v18, v105, v137
	v_fmac_f32_e32 v19, v105, v141
	v_fmac_f32_e32 v0, v105, v145
	v_add_u32_e32 v11, 128, v11
	s_add_i32 s19, s19, -1
	s_cmp_eq_u32 s19, 0
	s_cbranch_scc0 .LBB0_779
	ds_write2st64_b32 v4, v16, v17 offset0:80 offset1:82
	ds_write2st64_b32 v4, v18, v19 offset0:84 offset1:86
	ds_write_b32 v4, v0 offset:22528
	s_waitcnt lgkmcnt(0)
	s_barrier
	s_and_saveexec_b64 s[14:15], s[42:43]
	s_cbranch_execz .LBB0_691
	s_mul_i32 s22, s18, 0x1800
	v_add_u32_e32 v14, s22, v12
	v_ashrrev_i32_e32 v15, 31, v14
	s_mul_hi_i32 s19, s18, 5
	s_mul_i32 s18, s18, 5
	v_lshl_add_u64 v[14:15], v[14:15], 2, s[60:61]
	v_lshl_add_u64 v[12:13], v[12:13], 2, s[66:67]
	s_mov_b64 s[22:23], 0
	v_mov_b32_e32 v0, v25
	v_mov_b32_e32 v11, v158
